# mlstm_pre gate GEMV: row-prefetch register copies removed from the VALU-bound row loop (the SIMD's second wave already hides the row-load latency)
# speedup vs baseline: 1.0012x; 1.0011x over previous
.LBB0_400:
	v_lshl_add_u64 v[58:59], v[56:57], 0, s[24:25]
	s_waitcnt lgkmcnt(2)
	v_add_co_u32_e32 v62, vcc, 0xb100000, v58
	s_nop 1
	v_addc_co_u32_e32 v63, vcc, 0, v59, vcc
	global_load_dwordx4 v[58:61], v[62:63], off
	s_waitcnt lgkmcnt(0)
	global_load_dwordx4 v[72:75], v[62:63], off offset:1024
	global_load_dwordx4 v[76:79], v[62:63], off offset:2048
	global_load_dwordx4 v[80:83], v[62:63], off offset:3072
	s_waitcnt vmcnt(3)
	v_and_b32_e32 v63, 0xffff0000, v58
	v_and_b32_e32 v85, 0xffff0000, v59
	v_and_b32_e32 v89, 0xffff0000, v60
	v_and_b32_e32 v91, 0xffff0000, v61
	s_waitcnt vmcnt(2)
	v_and_b32_e32 v94, 0xffff0000, v72
	v_and_b32_e32 v98, 0xffff0000, v73
	v_and_b32_e32 v100, 0xffff0000, v74
	v_and_b32_e32 v104, 0xffff0000, v75
	v_and_b32_e32 v62, 16, v58
	v_lshlrev_b32_e32 v58, 16, v58
	v_and_b32_e32 v84, 16, v59
	v_lshlrev_b32_e32 v86, 16, v59
	v_and_b32_e32 v88, 16, v60
	v_lshlrev_b32_e32 v60, 16, v60
	v_and_b32_e32 v90, 16, v61
	v_lshlrev_b32_e32 v92, 16, v61
	v_and_b32_e32 v95, 16, v72
	v_lshlrev_b32_e32 v97, 16, v72
	v_and_b32_e32 v99, 16, v73
	v_lshlrev_b32_e32 v73, 16, v73
	v_and_b32_e32 v101, 16, v74
	v_lshlrev_b32_e32 v103, 16, v74
	v_and_b32_e32 v105, 16, v75
	v_lshlrev_b32_e32 v75, 16, v75
	v_mov_b32_e32 v59, v63
	v_mov_b32_e32 v87, v85
	v_mov_b32_e32 v61, v89
	v_mov_b32_e32 v93, v91
	v_mov_b32_e32 v96, v94
	v_mov_b32_e32 v72, v98
	v_mov_b32_e32 v102, v100
	v_mov_b32_e32 v74, v104
	v_pk_mul_f32 v[110:111], v[202:203], v[58:59]
	v_pk_mov_b32 v[62:63], v[62:63], v[58:59] op_sel:[1,0]
	v_pk_mul_f32 v[112:113], v[204:205], v[86:87]
	v_pk_mov_b32 v[84:85], v[84:85], v[86:87] op_sel:[1,0]
	v_pk_mul_f32 v[114:115], v[198:199], v[60:61]
	v_pk_mov_b32 v[88:89], v[88:89], v[60:61] op_sel:[1,0]
	v_pk_mul_f32 v[116:117], v[200:201], v[92:93]
	v_pk_mov_b32 v[90:91], v[90:91], v[92:93] op_sel:[1,0]
	v_pk_mov_b32 v[94:95], v[96:97], v[94:95] op_sel:[1,0]
	v_pk_mov_b32 v[98:99], v[72:73], v[98:99] op_sel:[1,0]
	v_pk_mov_b32 v[100:101], v[102:103], v[100:101] op_sel:[1,0]
	v_pk_mov_b32 v[104:105], v[74:75], v[104:105] op_sel:[1,0]
	v_pk_fma_f32 v[110:111], v[52:53], v[62:63], v[110:111]
	v_pk_fma_f32 v[112:113], v[54:55], v[84:85], v[112:113]
	v_pk_mul_f32 v[62:63], v[68:69], v[62:63]
	v_pk_mul_f32 v[84:85], v[70:71], v[84:85]
	v_pk_fma_f32 v[114:115], v[44:45], v[88:89], v[114:115]
	v_pk_fma_f32 v[116:117], v[46:47], v[90:91], v[116:117]
	v_pk_mul_f32 v[88:89], v[64:65], v[88:89]
	v_pk_mul_f32 v[90:91], v[66:67], v[90:91]
	v_pk_mul_f32 v[118:119], v[0:1], v[94:95]
	v_pk_mul_f32 v[94:95], v[16:17], v[94:95]
	v_pk_mul_f32 v[120:121], v[2:3], v[98:99]
	v_pk_mul_f32 v[98:99], v[18:19], v[98:99]
	v_pk_mul_f32 v[122:123], v[4:5], v[100:101]
	v_pk_mul_f32 v[124:125], v[6:7], v[104:105]
	v_pk_mul_f32 v[100:101], v[20:21], v[100:101]
	v_pk_add_f32 v[110:111], v[110:111], v[112:113]
	v_pk_fma_f32 v[58:59], v[178:179], v[58:59], v[62:63]
	v_pk_fma_f32 v[62:63], v[180:181], v[86:87], v[84:85]
	v_pk_add_f32 v[84:85], v[114:115], v[116:117]
	v_pk_fma_f32 v[60:61], v[174:175], v[60:61], v[88:89]
	v_pk_fma_f32 v[86:87], v[176:177], v[92:93], v[90:91]
	v_pk_fma_f32 v[88:89], v[196:197], v[96:97], v[118:119]
	v_pk_fma_f32 v[90:91], v[172:173], v[96:97], v[94:95]
	v_pk_fma_f32 v[92:93], v[194:195], v[72:73], v[120:121]
	v_pk_fma_f32 v[72:73], v[170:171], v[72:73], v[98:99]
	v_pk_fma_f32 v[94:95], v[192:193], v[102:103], v[122:123]
	v_pk_fma_f32 v[98:99], v[190:191], v[74:75], v[124:125]
	s_waitcnt vmcnt(1)
	v_and_b32_e32 v106, 0xffff0000, v76
	v_pk_mul_f32 v[104:105], v[22:23], v[104:105]
	v_pk_fma_f32 v[96:97], v[168:169], v[102:103], v[100:101]
	v_and_b32_e32 v100, 0xffff0000, v77
	v_pk_add_f32 v[84:85], v[110:111], v[84:85]
	v_pk_add_f32 v[88:89], v[88:89], v[92:93]
	v_pk_add_f32 v[92:93], v[94:95], v[98:99]
	v_and_b32_e32 v107, 16, v76
	v_lshlrev_b32_e32 v109, 16, v76
	v_pk_fma_f32 v[74:75], v[166:167], v[74:75], v[104:105]
	v_pk_add_f32 v[58:59], v[58:59], v[62:63]
	v_pk_add_f32 v[60:61], v[60:61], v[86:87]
	v_mov_b32_e32 v108, v106
	v_and_b32_e32 v101, 16, v77
	v_lshlrev_b32_e32 v77, 16, v77
	v_mov_b32_e32 v76, v100
	v_pk_add_f32 v[84:85], v[84:85], 0 op_sel_hi:[1,0]
	v_pk_add_f32 v[88:89], v[88:89], v[92:93]
	v_pk_mul_f32 v[62:63], v[188:189], v[108:109]
	v_pk_mul_f32 v[102:103], v[186:187], v[76:77]
	v_pk_mul_f32 v[104:105], v[162:163], v[76:77]
	v_and_b32_e32 v112, 0xffff0000, v78
	v_and_b32_e32 v120, 0xffff0000, v79
	v_pk_add_f32 v[84:85], v[84:85], v[88:89]
	v_pk_mov_b32 v[88:89], v[108:109], v[106:107] op_sel:[1,0]
	v_pk_mov_b32 v[76:77], v[76:77], v[100:101] op_sel:[1,0]
	v_pk_add_f32 v[58:59], v[58:59], v[60:61]
	v_pk_add_f32 v[60:61], v[90:91], v[72:73]
	v_pk_add_f32 v[72:73], v[96:97], v[74:75]
	v_pk_mul_f32 v[86:87], v[164:165], v[108:109]
	v_and_b32_e32 v113, 16, v78
	v_lshlrev_b32_e32 v115, 16, v78
	v_mov_b32_e32 v114, v112
	v_and_b32_e32 v121, 16, v79
	v_lshlrev_b32_e32 v79, 16, v79
	v_mov_b32_e32 v78, v120
	v_pk_fma_f32 v[62:63], v[8:9], v[88:89], v[62:63]
	v_pk_fma_f32 v[92:93], v[10:11], v[76:77], v[102:103]
	v_pk_add_f32 v[58:59], v[58:59], 0 op_sel_hi:[1,0]
	v_pk_add_f32 v[60:61], v[60:61], v[72:73]
	v_pk_mul_f32 v[116:117], v[184:185], v[114:115]
	v_pk_mul_f32 v[118:119], v[160:161], v[114:115]
	v_pk_mul_f32 v[122:123], v[182:183], v[78:79]
	v_pk_mul_f32 v[124:125], v[158:159], v[78:79]
	v_pk_add_f32 v[62:63], v[62:63], v[92:93]
	v_pk_mov_b32 v[92:93], v[114:115], v[112:113] op_sel:[1,0]
	v_pk_mov_b32 v[78:79], v[78:79], v[120:121] op_sel:[1,0]
	v_pk_add_f32 v[58:59], v[58:59], v[60:61] op_sel:[1,0] op_sel_hi:[0,1]
	v_pk_fma_f32 v[60:61], v[24:25], v[88:89], v[86:87]
	v_pk_fma_f32 v[72:73], v[26:27], v[76:77], v[104:105]
	v_pk_fma_f32 v[94:95], v[12:13], v[92:93], v[116:117]
	v_pk_fma_f32 v[98:99], v[14:15], v[78:79], v[122:123]
	v_pk_add_f32 v[60:61], v[60:61], v[72:73]
	v_pk_fma_f32 v[72:73], v[28:29], v[92:93], v[118:119]
	v_pk_fma_f32 v[74:75], v[30:31], v[78:79], v[124:125]
	v_pk_add_f32 v[94:95], v[94:95], v[98:99]
	v_pk_add_f32 v[72:73], v[72:73], v[74:75]
	s_waitcnt vmcnt(0)
	v_lshlrev_b32_e32 v126, 16, v80
	v_and_b32_e32 v127, 0xffff0000, v80
	v_lshlrev_b32_e32 v80, 16, v81
	v_and_b32_e32 v81, 0xffff0000, v81
	v_pk_add_f32 v[62:63], v[62:63], v[94:95]
	v_pk_add_f32 v[60:61], v[60:61], v[72:73]
	v_pk_add_f32 v[62:63], v[84:85], v[62:63]
	v_pk_mul_f32 v[84:85], v[32:33], v[126:127] op_sel:[0,1] op_sel_hi:[1,0]
	v_pk_mul_f32 v[94:95], v[34:35], v[80:81] op_sel:[0,1] op_sel_hi:[1,0]
	v_pk_add_f32 v[58:59], v[58:59], v[60:61]
	v_pk_mul_f32 v[60:61], v[40:41], v[126:127] op_sel:[0,1] op_sel_hi:[1,0]
	v_pk_mul_f32 v[72:73], v[42:43], v[80:81] op_sel:[0,1] op_sel_hi:[1,0]
	v_lshlrev_b32_e32 v228, 16, v82
	v_and_b32_e32 v229, 0xffff0000, v82
	v_lshlrev_b32_e32 v82, 16, v83
	v_and_b32_e32 v83, 0xffff0000, v83
	v_pk_fma_f32 v[84:85], v[142:143], v[126:127], v[84:85]
	v_pk_fma_f32 v[94:95], v[144:145], v[80:81], v[94:95]
	v_pk_fma_f32 v[60:61], v[150:151], v[126:127], v[60:61]
	v_pk_fma_f32 v[72:73], v[152:153], v[80:81], v[72:73]
	v_pk_add_f32 v[84:85], v[84:85], v[94:95]
	v_pk_mul_f32 v[94:95], v[36:37], v[228:229] op_sel:[0,1] op_sel_hi:[1,0]
	v_pk_mul_f32 v[98:99], v[38:39], v[82:83] op_sel:[0,1] op_sel_hi:[1,0]
	v_pk_add_f32 v[60:61], v[60:61], v[72:73]
	v_pk_mul_f32 v[72:73], v[48:49], v[228:229] op_sel:[0,1] op_sel_hi:[1,0]
	v_pk_mul_f32 v[74:75], v[50:51], v[82:83] op_sel:[0,1] op_sel_hi:[1,0]
	v_pk_fma_f32 v[94:95], v[146:147], v[228:229], v[94:95]
	v_pk_fma_f32 v[98:99], v[148:149], v[82:83], v[98:99]
	v_pk_fma_f32 v[72:73], v[154:155], v[228:229], v[72:73]
	v_pk_fma_f32 v[74:75], v[156:157], v[82:83], v[74:75]
	v_pk_add_f32 v[94:95], v[94:95], v[98:99]
	v_pk_add_f32 v[72:73], v[72:73], v[74:75]
	v_pk_add_f32 v[84:85], v[84:85], v[94:95]
	v_pk_add_f32 v[60:61], v[60:61], v[72:73]
	v_pk_add_f32 v[62:63], v[62:63], v[84:85]
	v_pk_add_f32 v[58:59], v[58:59], v[60:61]
	s_nop 1
	v_add_f32_dpp v62, v62, v62 quad_perm:[1,0,3,2] row_mask:0xf bank_mask:0xf
	v_add_f32_dpp v63, v63, v63 quad_perm:[1,0,3,2] row_mask:0xf bank_mask:0xf
	v_add_f32_dpp v58, v58, v58 quad_perm:[1,0,3,2] row_mask:0xf bank_mask:0xf
	v_add_f32_dpp v59, v59, v59 quad_perm:[1,0,3,2] row_mask:0xf bank_mask:0xf
	v_add_f32_dpp v62, v62, v62 quad_perm:[2,3,0,1] row_mask:0xf bank_mask:0xf
	v_add_f32_dpp v63, v63, v63 quad_perm:[2,3,0,1] row_mask:0xf bank_mask:0xf
	v_add_f32_dpp v58, v58, v58 quad_perm:[2,3,0,1] row_mask:0xf bank_mask:0xf
	v_add_f32_dpp v59, v59, v59 quad_perm:[2,3,0,1] row_mask:0xf bank_mask:0xf
	v_add_f32_dpp v62, v62, v62 row_half_mirror row_mask:0xf bank_mask:0xf
	v_add_f32_dpp v63, v63, v63 row_half_mirror row_mask:0xf bank_mask:0xf
	v_add_f32_dpp v58, v58, v58 row_half_mirror row_mask:0xf bank_mask:0xf
	v_add_f32_dpp v59, v59, v59 row_half_mirror row_mask:0xf bank_mask:0xf
	v_add_f32_dpp v62, v62, v62 row_mirror row_mask:0xf bank_mask:0xf
	v_add_f32_dpp v63, v63, v63 row_mirror row_mask:0xf bank_mask:0xf
	v_add_f32_dpp v58, v58, v58 row_mirror row_mask:0xf bank_mask:0xf
	v_add_f32_dpp v59, v59, v59 row_mirror row_mask:0xf bank_mask:0xf
	v_mov_b32_e32 v84, v62
	v_mov_b32_e32 v85, v63
	v_mov_b32_e32 v86, v58
	v_mov_b32_e32 v87, v59
	v_permlane16_swap_b32_e32 v62, v84
	v_permlane16_swap_b32_e32 v63, v85
	v_permlane16_swap_b32_e32 v58, v86
	v_permlane16_swap_b32_e32 v59, v87
	v_add_f32_e32 v62, v62, v84
	v_add_f32_e32 v63, v63, v85
	v_add_f32_e32 v58, v58, v86
	v_add_f32_e32 v59, v59, v87
	v_mov_b32_e32 v84, v62
	v_mov_b32_e32 v85, v63
	v_mov_b32_e32 v86, v58
	v_mov_b32_e32 v87, v59
	v_permlane32_swap_b32_e32 v62, v84
	v_permlane32_swap_b32_e32 v63, v85
	v_permlane32_swap_b32_e32 v58, v86
	v_permlane32_swap_b32_e32 v59, v87
	v_add_f32_e32 v62, v62, v84
	v_add_f32_e32 v63, v63, v85
	v_add_f32_e32 v58, v58, v86
	v_add_f32_e32 v59, v59, v87
	s_and_saveexec_b64 s[8:9], s[2:3]
	s_cbranch_execz .LBB0_399
	v_mov_b32_e32 v84, v63
	v_mov_b32_e32 v85, v62
	v_mov_b32_e32 v86, v59
	v_mov_b32_e32 v87, v58
	v_mov_b32_e32 v88, s12
	ds_write_b128 v88, v[84:87]
	s_branch .LBB0_399
